# scan slice loop top: fragment reads interleaved with the first MFMAs (15 in flight, counted lgkmcnt) instead of 30 up-front reads
# baseline (speedup 1.0000x reference)
; #define LAS __attribute__((address_space(3)))
; __device__ __forceinline__ float bflo(unsigned w) { return __uint_as_float(w << 16); }
; __device__ __forceinline__ float bfhi(unsigned w) { return __uint_as_float(w & 0xffff0000u); }
; __device__ __forceinline__ f32x4 mfma16(bf16x8 a, bf16x8 b, f32x4 c) { return __builtin_amdgcn_mfma_f32_16x16x32_bf16(a, b, c, 0, 0, 0); }
; __device__ __forceinline__ bf16x8 pack8(f32x4 a, f32x4 b) { v4u w; w.x = pk2(a[0], a[1]); w.y = pk2(a[2], a[3]); w.z = pk2(b[0], b[1]); w.w = pk2(b[2], b[3]); return __builtin_bit_cast(bf16x8, w); }
; __device__ __forceinline__ void scan_prompt_wg(const Params& P, LAS unsigned char* lds, int s, int h, int wave, int lane) {
;     ...
;             const LAS bf16x8* Wf = (const LAS bf16x8*)(ops + OPS_W) + lane; const LAS bf16x8* KT = (const LAS bf16x8*)(ops + OPS_KT) + lane;
;             const LAS bf16x8* QD = (const LAS bf16x8*)(ops + OPS_QD) + lane; const LAS bf16x8* QK = (const LAS bf16x8*)(ops + OPS_QK) + lane;
;             bf16x8 wv[8], qdv[8], qkv[6], ktv[8];
; #pragma unroll
;             for (int i = 0; i < 8; ++i) wv[i] = Wf[i * 64];
; #pragma unroll
;             for (int i = 0; i < 8; ++i) qdv[i] = QD[i * 64];
; #pragma unroll
;             for (int i = 0; i < 6; ++i) qkv[i] = QK[i * 64];
; #pragma unroll
;             for (int i = 0; i < 8; ++i) ktv[i] = KT[i * 64];
;             __builtin_amdgcn_sched_barrier(0);
;             bf16x8 Sb[2]; Sb[0] = pack8(S[0], S[1]); Sb[1] = pack8(S[2], S[3]);
;             f32x4 vn[4];
; #pragma unroll
;             for (int tau = 0; tau < 4; ++tau) { f32x4 av = {0.f, 0.f, 0.f, 0.f}; av = mfma16(wv[2 * tau], Sb[0], av); av = mfma16(wv[2 * tau + 1], Sb[1], av);
;                 const f32x4 u = {bflo(ua[tau].x), bfhi(ua[tau].x), bflo(ua[tau].y), bfhi(ua[tau].y)}; vn[tau] = u - av; }
;             bf16x8 Vb[2]; Vb[0] = pack8(vn[0], vn[1]); Vb[1] = pack8(vn[2], vn[3]);
;             f32x4 ao[4];
; #pragma unroll
;             for (int tau = 0; tau < 4; ++tau) { f32x4 a = {0.f, 0.f, 0.f, 0.f}; a = mfma16(qdv[2 * tau], Sb[0], a); a = mfma16(qdv[2 * tau + 1], Sb[1], a);
;                 a = mfma16(qkv[(tau < 2) ? tau : 2 * tau - 2], Vb[0], a); if (tau >= 2) a = mfma16(qkv[2 * tau - 1], Vb[1], a); ao[tau] = a; }
.LBB0_642:
	s_mul_i32 s0, s30, 0x7800
	v_add_u32_e32 v222, s0, v90
	ds_read_b128 v[92:95], v222
	ds_read_b128 v[96:99], v222 offset:1024
	ds_read_b128 v[100:103], v222 offset:2048
	ds_read_b128 v[104:107], v222 offset:3072
	ds_read_b128 v[108:111], v222 offset:4096
	ds_read_b128 v[112:115], v222 offset:5120
	ds_read_b128 v[116:119], v222 offset:6144
	ds_read_b128 v[120:123], v222 offset:7168
	ds_read_b128 v[124:127], v222 offset:16384
	ds_read_b128 v[128:131], v222 offset:17408
	ds_read_b128 v[132:135], v222 offset:18432
	ds_read_b128 v[136:139], v222 offset:19456
	ds_read_b128 v[140:143], v222 offset:20480
	ds_read_b128 v[144:147], v222 offset:21504
	ds_read_b128 v[148:151], v222 offset:22528
	s_add_i32 s0, s31, 1
	v_cvt_pk_bf16_f32 v214, v14, v15
	v_cvt_pk_bf16_f32 v215, v16, v17
	v_cvt_pk_bf16_f32 v216, v10, v11
	v_cvt_pk_bf16_f32 v217, v12, v13
	v_cvt_pk_bf16_f32 v218, v2, v3
	v_cvt_pk_bf16_f32 v219, v4, v5
	s_waitcnt lgkmcnt(14)
	v_mfma_f32_16x16x32_bf16 v[92:95], v[92:95], v[214:217], 0
	ds_read_b128 v[152:155], v222 offset:23552
	v_cvt_pk_bf16_f32 v220, v6, v7
	v_cvt_pk_bf16_f32 v221, v8, v9
	v_lshlrev_b32_e32 v33, 16, v50
	v_and_b32_e32 v50, 0xffff0000, v50
	s_waitcnt lgkmcnt(14)
	v_mfma_f32_16x16x32_bf16 v[92:95], v[96:99], v[218:221], v[92:95]
	ds_read_b128 v[156:159], v222 offset:24576
	s_bitcmp0_b32 s31, 0
	s_cselect_b32 s1, s29, 0x20200
	s_waitcnt vmcnt(0)
	v_pk_mul_f32 v[16:17], v[16:17], v[34:35] op_sel_hi:[1,0]
	s_waitcnt lgkmcnt(14)
	v_mfma_f32_16x16x32_bf16 v[96:99], v[100:103], v[214:217], 0
	ds_read_b128 v[160:163], v222 offset:25600
	v_lshlrev_b32_e32 v100, 16, v51
	v_and_b32_e32 v51, 0xffff0000, v51
	s_nop 0
	v_sub_f32_e32 v33, v33, v92
	s_waitcnt lgkmcnt(14)
	v_mfma_f32_16x16x32_bf16 v[96:99], v[104:107], v[218:221], v[96:99]
	ds_read_b128 v[166:169], v222 offset:26624
	v_sub_f32_e32 v105, v100, v94
	v_sub_f32_e32 v104, v51, v95
	v_sub_f32_e32 v106, v50, v93
	s_waitcnt lgkmcnt(14)
	v_mfma_f32_16x16x32_bf16 v[100:103], v[108:111], v[214:217], 0
	ds_read_b128 v[170:173], v222 offset:27648
	v_lshlrev_b32_e32 v107, 16, v48
	s_nop 2
	v_sub_f32_e32 v107, v107, v96
	v_lshlrev_b32_e32 v109, 16, v46
	s_waitcnt lgkmcnt(14)
	v_mfma_f32_16x16x32_bf16 v[92:95], v[112:115], v[218:221], v[100:103]
	ds_read_b128 v[174:177], v222 offset:28672
	v_and_b32_e32 v46, 0xffff0000, v46
	v_lshlrev_b32_e32 v110, 16, v47
	v_and_b32_e32 v47, 0xffff0000, v47
	v_and_b32_e32 v100, 0xffff0000, v48
	v_and_b32_e32 v102, 0xffff0000, v49
	v_lshlrev_b32_e32 v101, 16, v49
	v_sub_f32_e32 v103, v102, v99
	v_sub_f32_e32 v102, v100, v97
	s_waitcnt lgkmcnt(14)
	v_mfma_f32_16x16x32_bf16 v[48:51], v[116:119], v[214:217], 0
	ds_read_b128 v[178:181], v222 offset:29696
	v_sub_f32_e32 v108, v101, v98
	v_cvt_pk_bf16_f32 v100, v33, v106
	v_cvt_pk_bf16_f32 v101, v105, v104
	v_cvt_pk_bf16_f32 v102, v107, v102
	s_waitcnt lgkmcnt(11)
	v_mfma_f32_16x16x32_bf16 v[104:107], v[132:135], v[214:217], 0
	ds_read_b128 v[182:185], v222 offset:8192
	ds_read_b128 v[186:189], v222 offset:9216
	ds_read_b128 v[190:193], v222 offset:10240
	ds_read_b128 v[194:197], v222 offset:11264
	v_cvt_pk_bf16_f32 v103, v108, v103
	v_sub_f32_e32 v33, v47, v95
	v_sub_f32_e32 v108, v110, v94
	v_mfma_f32_16x16x32_bf16 v[48:51], v[120:123], v[218:221], v[48:51]
	v_sub_f32_e32 v110, v46, v93
	v_sub_f32_e32 v109, v109, v92
	v_lshlrev_b32_e32 v111, 16, v44
	v_mfma_f32_16x16x32_bf16 v[96:99], v[124:127], v[214:217], 0
	v_and_b32_e32 v112, 0xffff0000, v44
	v_and_b32_e32 v44, 0xffff0000, v45
	v_pk_mul_f32 v[14:15], v[14:15], v[34:35] op_sel_hi:[1,0]
	s_waitcnt lgkmcnt(14)
; #define LAS __attribute__((address_space(3)))
; __device__ __forceinline__ unsigned pk2(float lo, float hi) { return pg8::cvt_pk_bf16_v(lo, hi); }
; __device__ __forceinline__ float bflo(unsigned w) { return __uint_as_float(w << 16); }
; __device__ __forceinline__ float bfhi(unsigned w) { return __uint_as_float(w & 0xffff0000u); }
; __device__ __forceinline__ f32x4 mfma16(bf16x8 a, bf16x8 b, f32x4 c) { return __builtin_amdgcn_mfma_f32_16x16x32_bf16(a, b, c, 0, 0, 0); }
; __device__ __forceinline__ bf16x8 pack8(f32x4 a, f32x4 b) { v4u w; w.x = pk2(a[0], a[1]); w.y = pk2(a[2], a[3]); w.z = pk2(b[0], b[1]); w.w = pk2(b[2], b[3]); return __builtin_bit_cast(bf16x8, w); }
; __device__ __forceinline__ void scan_prompt_wg(const Params& P, LAS unsigned char* lds, int s, int h, int wave, int lane) {
;     ...
;             for (int tau = 0; tau < 4; ++tau) { f32x4 av = {0.f, 0.f, 0.f, 0.f}; av = mfma16(wv[2 * tau], Sb[0], av); av = mfma16(wv[2 * tau + 1], Sb[1], av);
;                 const f32x4 u = {bflo(ua[tau].x), bfhi(ua[tau].x), bflo(ua[tau].y), bfhi(ua[tau].y)}; vn[tau] = u - av; }
;             bf16x8 Vb[2]; Vb[0] = pack8(vn[0], vn[1]); Vb[1] = pack8(vn[2], vn[3]);
;             f32x4 ao[4];
; #pragma unroll
;             for (int tau = 0; tau < 4; ++tau) { f32x4 a = {0.f, 0.f, 0.f, 0.f}; a = mfma16(qdv[2 * tau], Sb[0], a); a = mfma16(qdv[2 * tau + 1], Sb[1], a);
;                 a = mfma16(qkv[(tau < 2) ? tau : 2 * tau - 2], Vb[0], a); if (tau >= 2) a = mfma16(qkv[2 * tau - 1], Vb[1], a); ao[tau] = a; }
; #pragma unroll
;             for (int tau = 0; tau < 4; ++tau) { f32x4 a = S[tau] * gt; a = mfma16(ktv[2 * tau], Vb[0], a); a = mfma16(ktv[2 * tau + 1], Vb[1], a); S[tau] = a; }
;             LAS unsigned char* ot = lds + ((n & 1) ? OT_B : OT_A) + e * 2;
; #pragma unroll
;             for (int tau = 0; tau < 4; ++tau)
; #pragma unroll
;                 for (int r = 0; r < 4; ++r) *(LAS unsigned short*)(ot + (16 * tau + 4 * q4 + r) * 128) = (unsigned short)(pk2(ao[tau][r], 0.f) & 0xffffu);
;             gt = gtn;
; #pragma unroll
;             for (int tau = 0; tau < 4; ++tau) { ua[tau] = ub[tau]; ub[tau] = uc[tau]; }
;             slot = (slot == SR_NS - 1) ? 0 : slot + 1;
;             asm volatile("s_waitcnt lgkmcnt(0)" ::: "memory");
;             SCAN_BAR();
	v_mfma_f32_16x16x32_bf16 v[92:95], v[136:139], v[218:221], v[104:107]
	ds_read_b128 v[198:201], v222 offset:12288
	v_mul_f32_e64 v12, v12, v34
	v_mul_f32_e64 v13, v13, v34
	v_pk_mul_f32 v[10:11], v[10:11], v[34:35] op_sel_hi:[1,0]
	v_pk_mul_f32 v[4:5], v[4:5], v[34:35] op_sel_hi:[1,0]
	v_lshlrev_b32_e32 v104, 16, v45
	v_mfma_f32_16x16x32_bf16 v[96:99], v[128:131], v[218:221], v[96:99]
	v_sub_f32_e32 v105, v44, v51
	v_pk_mul_f32 v[2:3], v[2:3], v[34:35] op_sel_hi:[1,0]
	v_pk_mul_f32 v[8:9], v[8:9], v[34:35] op_sel_hi:[1,0]
	ds_read_b128 v[202:205], v222 offset:13312
	ds_read_b128 v[206:209], v222 offset:14336
	ds_read_b128 v[210:213], v222 offset:15360
	s_waitcnt lgkmcnt(12)
	v_mfma_f32_16x16x32_bf16 v[44:47], v[160:163], v[100:103], v[92:95]
	v_mul_f32_e64 v6, v6, v34
	v_mul_f32_e64 v7, v7, v34
	v_lshl_add_u64 v[30:31], v[30:31], 0, s[16:17]
	s_mov_b32 s31, s0
	v_sub_f32_e32 v95, v104, v50
	v_sub_f32_e32 v94, v112, v49
	v_sub_f32_e32 v104, v111, v48
	v_mfma_f32_16x16x32_bf16 v[48:51], v[140:143], v[214:217], 0
	v_cvt_pk_bf16_f32 v94, v104, v94
	v_cvt_pk_bf16_f32 v95, v95, v105
	v_cvt_pk_bf16_f32 v93, v108, v33
	v_mfma_f32_16x16x32_bf16 v[96:99], v[156:159], v[100:103], v[96:99]
	v_add_u32_e32 v33, s1, v21
	v_cvt_pk_bf16_f32 v92, v109, v110
	s_add_i32 s1, s30, 1
	v_mfma_f32_16x16x32_bf16 v[48:51], v[144:147], v[218:221], v[48:51]
	s_cmp_lg_u32 s30, 3
	s_nop 2
	v_cvt_pk_bf16_f32 v34, v96, s0
	v_add_u32_e32 v96, v33, v74
	v_mfma_f32_16x16x32_bf16 v[104:107], v[148:151], v[214:217], 0
	ds_write_b16 v96, v34
	v_cvt_pk_bf16_f32 v34, v97, s0
	v_add_u32_e32 v96, v33, v75
	s_waitcnt lgkmcnt(12)
	v_mfma_f32_16x16x32_bf16 v[48:51], v[166:169], v[100:103], v[48:51]
	ds_write_b16 v96, v34
	v_cvt_pk_bf16_f32 v34, v98, s0
	v_add_u32_e32 v96, v33, v76
	v_mfma_f32_16x16x32_bf16 v[104:107], v[152:155], v[218:221], v[104:107]
	ds_write_b16 v96, v34
	v_cvt_pk_bf16_f32 v34, v99, s0
	v_add_u32_e32 v96, v33, v77
	s_waitcnt lgkmcnt(13)
	v_mfma_f32_16x16x32_bf16 v[48:51], v[170:173], v[92:95], v[48:51]
	ds_write_b16 v96, v34
	v_cvt_pk_bf16_f32 v34, v44, s0
	v_add_u32_e32 v44, v33, v78
	s_waitcnt lgkmcnt(13)
	v_mfma_f32_16x16x32_bf16 v[104:107], v[174:177], v[100:103], v[104:107]
	ds_write_b16 v44, v34
	v_cvt_pk_bf16_f32 v34, v45, s0
	v_add_u32_e32 v44, v33, v79
	ds_write_b16 v44, v34
	v_cvt_pk_bf16_f32 v34, v46, s0
	v_add_u32_e32 v44, v33, v80
	ds_write_b16 v44, v34
	v_cvt_pk_bf16_f32 v34, v47, s0
	v_add_u32_e32 v44, v33, v81
	s_waitcnt lgkmcnt(14)
	v_mfma_f32_16x16x32_bf16 v[104:107], v[178:181], v[92:95], v[104:107]
	ds_write_b16 v44, v34
	v_cvt_pk_bf16_f32 v34, v48, s0
	v_add_u32_e32 v44, v33, v82
	ds_write_b16 v44, v34
	v_cvt_pk_bf16_f32 v34, v49, s0
	v_add_u32_e32 v44, v33, v83
	ds_write_b16 v44, v34
	v_cvt_pk_bf16_f32 v34, v50, s0
	v_add_u32_e32 v44, v33, v84
	ds_write_b16 v44, v34
	v_cvt_pk_bf16_f32 v34, v51, s0
	v_add_u32_e32 v44, v33, v85
	ds_write_b16 v44, v34
	v_cvt_pk_bf16_f32 v34, v104, s0
	v_add_u32_e32 v44, v33, v86
	v_mfma_f32_16x16x32_bf16 v[14:17], v[182:185], v[100:103], v[14:17]
	ds_write_b16 v44, v34
	v_cvt_pk_bf16_f32 v34, v105, s0
	v_add_u32_e32 v44, v33, v87
	s_waitcnt lgkmcnt(14)
	v_mfma_f32_16x16x32_bf16 v[10:13], v[190:193], v[100:103], v[10:13]
	ds_write_b16 v44, v34
	v_cvt_pk_bf16_f32 v34, v106, s0
	v_add_u32_e32 v44, v33, v88
	v_mfma_f32_16x16x32_bf16 v[2:5], v[198:201], v[100:103], v[2:5]
	ds_write_b16 v44, v34
	v_cvt_pk_bf16_f32 v34, v107, s0
	v_add_u32_e32 v33, v33, v89
	v_mfma_f32_16x16x32_bf16 v[6:9], v[206:209], v[100:103], v[6:9]
	ds_write_b16 v33, v34
	s_waitcnt lgkmcnt(0)
	s_cselect_b32 s30, s1, 0
	v_mfma_f32_16x16x32_bf16 v[14:17], v[186:189], v[92:95], v[14:17]
	s_barrier
	v_mfma_f32_16x16x32_bf16 v[10:13], v[194:197], v[92:95], v[10:13]
	s_add_u32 s14, s14, 32
	s_addc_u32 s15, s15, 0
	s_cmpk_eq_i32 s0, 0x80
	v_mfma_f32_16x16x32_bf16 v[2:5], v[202:205], v[92:95], v[2:5]
	v_mov_b64_e32 v[50:51], v[42:43]
	v_mov_b64_e32 v[48:49], v[40:41]
	v_mov_b64_e32 v[46:47], v[38:39]
	s_waitcnt lgkmcnt(14)
	v_mfma_f32_16x16x32_bf16 v[6:9], v[210:213], v[92:95], v[6:9]
	v_mov_b64_e32 v[44:45], v[36:37]
	v_mov_b32_e32 v34, v91
	s_cbranch_scc1 .LBB0_653
